# lever 8 MFMA-shadow fill: selection fast path u=1 exp2/cvt interleaved under the u=0 PV fp8 MFMAs
# speedup vs baseline: 1.0078x; 1.0078x over previous
; __device__ __forceinline__ void nsa_unit(const Params& p, int bg, int jq, LAS unsigned char* lds, int wave, int lane, bool build_lut) {
;     ...
; #pragma unroll
;                     for (int u = 0; u < 2; ++u)
; #pragma unroll
;                         for (int kt = 0; kt < 4; ++kt)
; #pragma unroll
;                             for (int e = 0; e < 4; ++e) sc[u][kt][e] = fast_exp2(sc[u][kt][e]);
;                 } else {
;                     float mx = NEG_INF;
; #pragma unroll
;                     for (int u = 0; u < 2; ++u)
; #pragma unroll
;                         for (int kt = 0; kt < 4; ++kt)
; #pragma unroll
;                             for (int e = 0; e < 4; ++e) {
;                                 const int d = tqg - 64 * nb[u] - 16 * kt - 4 * fq - e;
;                                 const bool okk = ok[u] && d >= 0;
;                                 const float v = okk ? (sc[u][kt][e] + lutr16[min(max(d, 0), 128)]) : NEG_INF;
;                                 sc[u][kt][e] = v; mx = fmaxf(mx, v);
;                             }
;                     { auto t1 = __builtin_amdgcn_permlane16_swap(__float_as_uint(mx), __float_as_uint(mx), false, false); mx = fmaxf(__uint_as_float(t1[0]), __uint_as_float(t1[1])); mx = xhalf_max(mx); }
;                     if (__any(mx > m + 2.0f)) {
;                         const float mnew = (mx > m + 2.0f) ? mx : m;
;                         const float alpha = fast_exp2(m - mnew);
;                         lacc = lacc * alpha; m = mnew;
; #pragma unroll
;                         for (int dt = 0; dt < 4; ++dt) o[dt] = o[dt] * alpha;
;                     }
;                     const float cexp = m - 6.0f;
; #pragma unroll
;                     for (int u = 0; u < 2; ++u)
; #pragma unroll
;                         for (int kt = 0; kt < 4; ++kt)
; #pragma unroll
;                             for (int e = 0; e < 4; ++e) sc[u][kt][e] = fast_exp2(sc[u][kt][e] - cexp);
;                 }
; #pragma unroll
;                 for (int u = 0; u < 2; ++u) {
;                     const long pb0 = pack_fp8x8(sc[u][0][0], sc[u][0][1], sc[u][0][2], sc[u][0][3], sc[u][1][0], sc[u][1][1], sc[u][1][2], sc[u][1][3]);
;                     const long pb1 = pack_fp8x8(sc[u][2][0], sc[u][2][1], sc[u][2][2], sc[u][2][3], sc[u][3][0], sc[u][3][1], sc[u][3][2], sc[u][3][3]);
; #pragma unroll
.Lsel_fast_exp:
	v_exp_f32_e32 v116, v116
	v_exp_f32_e32 v117, v117
	v_exp_f32_e32 v118, v118
	v_exp_f32_e32 v119, v119
	v_exp_f32_e32 v108, v108
	v_exp_f32_e32 v109, v109
	v_exp_f32_e32 v110, v110
	v_exp_f32_e32 v111, v111
	v_exp_f32_e32 v96, v96
	v_exp_f32_e32 v97, v97
	v_exp_f32_e32 v98, v98
	v_exp_f32_e32 v99, v99
	v_exp_f32_e32 v100, v100
	v_exp_f32_e32 v101, v101
	v_exp_f32_e32 v102, v102
	v_exp_f32_e32 v103, v103
	v_cvt_pk_fp8_f32 v244, v116, v117
	v_cvt_pk_fp8_f32 v245, v108, v109
	v_cvt_pk_fp8_f32 v246, v96, v97
	v_cvt_pk_fp8_f32 v247, v100, v101
	v_cvt_pk_fp8_f32 v244, v118, v119 op_sel:[0,0,1]
	v_cvt_pk_fp8_f32 v245, v110, v111 op_sel:[0,0,1]
	v_cvt_pk_fp8_f32 v246, v98, v99 op_sel:[0,0,1]
	v_cvt_pk_fp8_f32 v247, v102, v103 op_sel:[0,0,1]
	s_add_i32 s43, s43, 8
	s_add_i32 s40, s40, 2
	s_cmp_ge_u32 s44, s41
	s_cbranch_scc1 .Lsel_fast_pv_last
	s_waitcnt vmcnt(15)
	v_mfma_f32_16x16x32_fp8_fp8 v[48:51], v[84:85], v[244:245], v[48:51]
	v_exp_f32_e32 v112, v112
	v_exp_f32_e32 v113, v113
	v_mfma_f32_16x16x32_fp8_fp8 v[52:55], v[242:243], v[244:245], v[52:55]
	v_exp_f32_e32 v114, v114
	v_exp_f32_e32 v115, v115
	s_waitcnt vmcnt(14)
	v_mfma_f32_16x16x32_fp8_fp8 v[44:47], v[80:81], v[244:245], v[44:47]
	v_exp_f32_e32 v104, v104
	v_exp_f32_e32 v105, v105
	s_waitcnt vmcnt(13)
	v_mfma_f32_16x16x32_fp8_fp8 v[40:43], v[76:77], v[244:245], v[40:43]
	v_exp_f32_e32 v106, v106
	v_exp_f32_e32 v107, v107
	s_waitcnt vmcnt(12)
	v_mfma_f32_16x16x32_fp8_fp8 v[24:27], v[72:73], v[244:245], v[24:27]
	v_exp_f32_e32 v92, v92
	v_exp_f32_e32 v93, v93
	v_mfma_f32_16x16x32_fp8_fp8 v[48:51], v[86:87], v[246:247], v[48:51]
	v_exp_f32_e32 v94, v94
	v_exp_f32_e32 v95, v95
	v_mfma_f32_16x16x32_fp8_fp8 v[44:47], v[82:83], v[246:247], v[44:47]
	v_exp_f32_e32 v88, v88
	v_exp_f32_e32 v89, v89
	v_mfma_f32_16x16x32_fp8_fp8 v[40:43], v[78:79], v[246:247], v[40:43]
	v_exp_f32_e32 v90, v90
	v_exp_f32_e32 v91, v91
	v_mfma_f32_16x16x32_fp8_fp8 v[24:27], v[74:75], v[246:247], v[24:27]
	v_cvt_pk_fp8_f32 v248, v112, v113
	v_cvt_pk_fp8_f32 v249, v104, v105
	v_mfma_f32_16x16x32_fp8_fp8 v[52:55], v[242:243], v[246:247], v[52:55]
	v_cvt_pk_fp8_f32 v248, v114, v115 op_sel:[0,0,1]
	v_cvt_pk_fp8_f32 v249, v106, v107 op_sel:[0,0,1]
	v_cvt_pk_fp8_f32 v250, v92, v93
	v_cvt_pk_fp8_f32 v251, v88, v89
	v_cvt_pk_fp8_f32 v250, v94, v95 op_sel:[0,0,1]
	v_cvt_pk_fp8_f32 v251, v90, v91 op_sel:[0,0,1]
	s_waitcnt vmcnt(11)
	v_mfma_f32_16x16x32_fp8_fp8 v[48:51], v[68:69], v[248:249], v[48:51]
	v_mfma_f32_16x16x32_fp8_fp8 v[52:55], v[242:243], v[248:249], v[52:55]
	s_waitcnt vmcnt(10)
	v_mfma_f32_16x16x32_fp8_fp8 v[44:47], v[64:65], v[248:249], v[44:47]
	s_waitcnt vmcnt(9)
	v_mfma_f32_16x16x32_fp8_fp8 v[40:43], v[60:61], v[248:249], v[40:43]
	s_waitcnt vmcnt(8)
	v_mfma_f32_16x16x32_fp8_fp8 v[24:27], v[56:57], v[248:249], v[24:27]
	v_mfma_f32_16x16x32_fp8_fp8 v[48:51], v[70:71], v[250:251], v[48:51]
	v_mfma_f32_16x16x32_fp8_fp8 v[44:47], v[66:67], v[250:251], v[44:47]
	v_mfma_f32_16x16x32_fp8_fp8 v[40:43], v[62:63], v[250:251], v[40:43]
	v_mfma_f32_16x16x32_fp8_fp8 v[24:27], v[58:59], v[250:251], v[24:27]
	v_mfma_f32_16x16x32_fp8_fp8 v[52:55], v[242:243], v[250:251], v[52:55]
	s_mov_b32 s8, s18
	s_mov_b32 s22, s16
	s_branch .LBB0_1200
.Lsel_fast_pv_last:
	s_waitcnt vmcnt(7)
	v_mfma_f32_16x16x32_fp8_fp8 v[48:51], v[84:85], v[244:245], v[48:51]
	v_exp_f32_e32 v112, v112
	v_exp_f32_e32 v113, v113
	v_mfma_f32_16x16x32_fp8_fp8 v[52:55], v[242:243], v[244:245], v[52:55]
	v_exp_f32_e32 v114, v114
	v_exp_f32_e32 v115, v115
	s_waitcnt vmcnt(6)
	v_mfma_f32_16x16x32_fp8_fp8 v[44:47], v[80:81], v[244:245], v[44:47]
	v_exp_f32_e32 v104, v104
	v_exp_f32_e32 v105, v105
	s_waitcnt vmcnt(5)
	v_mfma_f32_16x16x32_fp8_fp8 v[40:43], v[76:77], v[244:245], v[40:43]
	v_exp_f32_e32 v106, v106
	v_exp_f32_e32 v107, v107
	s_waitcnt vmcnt(4)
	v_mfma_f32_16x16x32_fp8_fp8 v[24:27], v[72:73], v[244:245], v[24:27]
	v_exp_f32_e32 v92, v92
	v_exp_f32_e32 v93, v93
	v_mfma_f32_16x16x32_fp8_fp8 v[48:51], v[86:87], v[246:247], v[48:51]
	v_exp_f32_e32 v94, v94
	v_exp_f32_e32 v95, v95
	v_mfma_f32_16x16x32_fp8_fp8 v[44:47], v[82:83], v[246:247], v[44:47]
	v_exp_f32_e32 v88, v88
	v_exp_f32_e32 v89, v89
	v_mfma_f32_16x16x32_fp8_fp8 v[40:43], v[78:79], v[246:247], v[40:43]
	v_exp_f32_e32 v90, v90
	v_exp_f32_e32 v91, v91
	v_mfma_f32_16x16x32_fp8_fp8 v[24:27], v[74:75], v[246:247], v[24:27]
	v_cvt_pk_fp8_f32 v248, v112, v113
	v_cvt_pk_fp8_f32 v249, v104, v105
	v_mfma_f32_16x16x32_fp8_fp8 v[52:55], v[242:243], v[246:247], v[52:55]
	v_cvt_pk_fp8_f32 v248, v114, v115 op_sel:[0,0,1]
	v_cvt_pk_fp8_f32 v249, v106, v107 op_sel:[0,0,1]
	v_cvt_pk_fp8_f32 v250, v92, v93
	v_cvt_pk_fp8_f32 v251, v88, v89
	v_cvt_pk_fp8_f32 v250, v94, v95 op_sel:[0,0,1]
	v_cvt_pk_fp8_f32 v251, v90, v91 op_sel:[0,0,1]
	s_waitcnt vmcnt(3)
	v_mfma_f32_16x16x32_fp8_fp8 v[48:51], v[68:69], v[248:249], v[48:51]
	v_mfma_f32_16x16x32_fp8_fp8 v[52:55], v[242:243], v[248:249], v[52:55]
	s_waitcnt vmcnt(2)
	v_mfma_f32_16x16x32_fp8_fp8 v[44:47], v[64:65], v[248:249], v[44:47]
	s_waitcnt vmcnt(1)
	v_mfma_f32_16x16x32_fp8_fp8 v[40:43], v[60:61], v[248:249], v[40:43]
	s_waitcnt vmcnt(0)
	v_mfma_f32_16x16x32_fp8_fp8 v[24:27], v[56:57], v[248:249], v[24:27]
	v_mfma_f32_16x16x32_fp8_fp8 v[48:51], v[70:71], v[250:251], v[48:51]
	v_mfma_f32_16x16x32_fp8_fp8 v[44:47], v[66:67], v[250:251], v[44:47]
	v_mfma_f32_16x16x32_fp8_fp8 v[40:43], v[62:63], v[250:251], v[40:43]
	v_mfma_f32_16x16x32_fp8_fp8 v[24:27], v[58:59], v[250:251], v[24:27]
	v_mfma_f32_16x16x32_fp8_fp8 v[52:55], v[242:243], v[250:251], v[52:55]
	s_branch .LBB0_1278
